# r48 layout variant: gdn_pre chunk-loop code shifted by 4 bytes, everything after it by 8 (code alignment tuning)
# speedup vs baseline: 1.0023x; 1.0003x over previous
.LBB0_292:
	s_or_b64 exec, exec, s[0:1]
	s_waitcnt vmcnt(2)
	v_mul_lo_u32 v4, v53, 24
	v_sub_u32_e32 v4, v37, v4
	v_lshlrev_b32_e32 v5, 5, v4
	v_lshlrev_b32_e32 v4, 3, v4
	v_and_b32_e32 v39, 56, v4
	v_mul_lo_u32 v4, v55, 24
	v_sub_u32_e32 v2, v2, v4
	v_lshlrev_b32_e32 v4, 5, v2
	v_lshlrev_b32_e32 v2, 3, v2
	v_and_b32_e32 v46, 56, v2
	v_mul_lo_u32 v2, v60, 24
	s_movk_i32 s0, 0xc00
	v_sub_u32_e32 v2, v8, v2
	v_cmp_gt_i32_e64 s[10:11], s0, v37
	s_movk_i32 s0, 0x580
	v_and_b32_e32 v6, 0xffffff00, v4
	v_lshlrev_b32_e32 v4, 5, v2
	v_lshlrev_b32_e32 v2, 3, v2
	v_cmp_gt_i32_e64 s[0:1], s0, v37
	v_and_b32_e32 v48, 56, v2
	v_mul_lo_u32 v2, v61, 24
	v_writelane_b32 v254, s0, 15
	v_sub_u32_e32 v2, v10, v2
	v_mul_f32_e32 v3, 0x3fb8aa3b, v3
	v_ashrrev_i32_e32 v68, 6, v37
	v_writelane_b32 v254, s1, 16
	s_mov_b32 s0, 0x55555556
	v_and_b32_e32 v8, 0xffffff00, v4
	v_lshlrev_b32_e32 v4, 5, v2
	v_exp_f32_e32 v62, v3
	v_mul_hi_i32 v3, v68, s0
	v_and_b32_e32 v10, 0xffffff00, v4
	v_lshrrev_b32_e32 v4, 31, v3
	v_add_u32_e32 v3, v3, v4
	v_lshl_add_u32 v3, v3, 1, v3
	v_sub_u32_e32 v3, v68, v3
	v_add_u32_e32 v4, 2, v68
	v_readlane_b32 s52, v253, 9
	v_cmp_lt_i32_e64 s[24:25], 0, v3
	v_and_b32_e32 v12, 0xffffff00, v5
	v_and_b32_e32 v36, 31, v37
	v_mov_b32_e32 v5, s52
	v_cmp_gt_u32_e64 s[0:1], 5, v4
	v_cndmask_b32_e64 v45, 0, 32, s[24:25]
	v_lshrrev_b32_e32 v14, 3, v37
	v_cmp_lt_u32_e64 s[22:23], 4, v4
	v_cndmask_b32_e64 v4, 0, v5, s[0:1]
	v_or_b32_e32 v5, v45, v36
	v_and_b32_e32 v47, 4, v14
	v_mul_u32_u24_e32 v5, 0x110, v5
	v_lshlrev_b32_e32 v40, 2, v47
	v_cmp_eq_u32_e64 s[24:25], 2, v3
	v_readlane_b32 s3, v253, 11
	v_add3_u32 v69, v4, v5, v40
	v_cndmask_b32_e64 v3, 0, 32, s[24:25]
	v_mov_b32_e32 v5, s3
	v_readlane_b32 s3, v253, 10
	v_or_b32_e32 v3, v3, v36
	v_readlane_b32 s36, v253, 6
	v_mov_b32_e32 v14, s3
	v_lshlrev_b32_e32 v4, 2, v3
	v_cndmask_b32_e64 v5, v5, v14, s[0:1]
	v_and_b32_e32 v71, 15, v37
	v_bfe_u32 v16, v37, 4, 2
	v_readlane_b32 s3, v253, 12
	v_lshlrev_b32_e32 v2, 3, v2
	v_ashrrev_i32_e32 v44, 3, v37
	v_add_u32_e32 v70, s36, v4
	v_add_u32_e32 v14, v5, v4
	v_lshl_add_u32 v4, v68, 10, s3
	v_lshlrev_b32_e32 v5, 8, v16
	v_lshlrev_b32_e32 v17, 2, v71
	s_movk_i32 s38, 0xffe0
	v_and_b32_e32 v50, 56, v2
	v_lshlrev_b32_e32 v2, 3, v37
	v_add3_u32 v75, v4, v5, v17
	v_bfi_b32 v4, s38, v44, v37
	s_movk_i32 s3, 0xff
	v_and_b32_e32 v2, 56, v2
	v_mul_lo_u32 v4, v4, s79
	v_cmp_lt_u32_e64 s[24:25], s3, v37
	s_lshl_b32 s3, s88, 7
	s_lshl_b32 s27, s27, 5
	v_add3_u32 v76, s77, v4, v40
	s_or_b32 s74, s3, s27
	v_mul_lo_u32 v4, v44, s64
	v_lshlrev_b32_e32 v51, 2, v2
	v_readlane_b32 s27, v253, 13
	v_lshlrev_b32_e32 v63, 2, v37
	v_readlane_b32 s34, v253, 8
	v_add3_u32 v77, s27, v4, v51
	v_mul_lo_u32 v4, v44, s79
	s_movk_i32 s0, 0x80
	v_add_u32_e32 v4, 0, v4
	v_lshlrev_b32_e32 v52, 2, v44
	s_movk_i32 s3, 0xfef4
	v_add_u32_e32 v66, s34, v63
	v_subrev_co_u32_e64 v38, s[0:1], s0, v37
	v_add_u32_e32 v78, v4, v51
	v_add_u32_e32 v79, s34, v52
	v_mad_u64_u32 v[4:5], s[34:35], v44, s3, v[4:5]
	s_xor_b64 s[20:21], s[0:1], -1
	s_movk_i32 s0, 0x680
	v_cmp_gt_i32_e64 s[34:35], 1, v37
	v_cmp_gt_i32_e64 s[0:1], s0, v37
	s_and_b64 s[82:83], s[20:21], s[0:1]
	v_writelane_b32 v254, s34, 17
	v_cmp_eq_u32_e64 s[0:1], 0, v71
	v_or_b32_e32 v45, v45, v47
	v_writelane_b32 v254, s35, 18
	v_cmp_gt_i32_e64 s[34:35], 2, v37
	v_cndmask_b32_e64 v92, 0, 1.0, s[0:1]
	v_cmp_eq_u32_e64 s[0:1], 1, v71
	v_writelane_b32 v254, s34, 19
	v_cmp_gt_u32_e64 s[40:41], v45, v3
	v_cndmask_b32_e64 v93, 0, 1.0, s[0:1]
	v_writelane_b32 v254, s35, 20
	v_cmp_gt_i32_e64 s[34:35], 4, v37
	v_cmp_eq_u32_e64 s[0:1], 2, v71
	v_or_b32_e32 v54, 1, v45
	v_writelane_b32 v254, s34, 21
	v_cndmask_b32_e64 v94, 0, 1.0, s[0:1]
	v_cmp_eq_u32_e64 s[0:1], 3, v71
	v_writelane_b32 v254, s35, 22
	v_cmp_gt_i32_e64 s[34:35], 8, v37
	v_cndmask_b32_e64 v95, 0, 1.0, s[0:1]
	v_cmp_eq_u32_e64 s[0:1], 4, v71
	v_writelane_b32 v254, s34, 23
	v_readlane_b32 s37, v253, 7
	v_cndmask_b32_e64 v96, 0, 1.0, s[0:1]
	v_cmp_eq_u32_e64 s[0:1], 5, v71
	v_writelane_b32 v254, s35, 24
	v_cmp_gt_i32_e64 s[34:35], 16, v37
	v_cndmask_b32_e64 v97, 0, 1.0, s[0:1]
	v_cmp_eq_u32_e64 s[0:1], 6, v71
	v_writelane_b32 v254, s34, 25
	v_max_i32_e32 v57, 0x480, v38
	v_cndmask_b32_e64 v98, 0, 1.0, s[0:1]
	v_cmp_eq_u32_e64 s[0:1], 7, v71
	v_writelane_b32 v254, s35, 26
	v_cmp_gt_i32_e64 s[34:35], 32, v37
	v_cndmask_b32_e64 v99, 0, 1.0, s[0:1]
	v_cmp_eq_u32_e64 s[0:1], 8, v71
	v_writelane_b32 v254, s34, 27
	v_add_u32_e32 v57, 0x80, v57
	v_cndmask_b32_e64 v100, 0, 1.0, s[0:1]
	v_cmp_eq_u32_e64 s[0:1], 9, v71
	v_writelane_b32 v254, s35, 28
	v_writelane_b32 v254, s40, 29
	v_cndmask_b32_e64 v101, 0, 1.0, s[0:1]
	v_cmp_eq_u32_e64 s[0:1], 10, v71
	v_writelane_b32 v254, s41, 30
	v_cmp_ge_u32_e64 s[40:41], v54, v3
	v_cndmask_b32_e64 v102, 0, 1.0, s[0:1]
	v_cmp_eq_u32_e64 s[0:1], 11, v71
	v_lshlrev_b32_e32 v54, 2, v54
	v_writelane_b32 v254, s40, 31
	v_cndmask_b32_e64 v103, 0, 1.0, s[0:1]
	v_cmp_eq_u32_e64 s[0:1], 12, v71
	v_add_u32_e32 v87, s36, v54
	v_add_u32_e32 v88, s37, v54
	v_or_b32_e32 v54, 2, v45
	v_cndmask_b32_e64 v104, 0, 1.0, s[0:1]
	v_cmp_eq_u32_e64 s[0:1], 13, v71
	v_writelane_b32 v254, s41, 32
	v_cmp_ge_u32_e64 s[40:41], v54, v3
	v_cndmask_b32_e64 v105, 0, 1.0, s[0:1]
	v_cmp_eq_u32_e64 s[0:1], 14, v71
	v_writelane_b32 v254, s40, 33
	v_lshlrev_b32_e32 v56, 2, v54
	v_cndmask_b32_e64 v106, 0, 1.0, s[0:1]
	v_cmp_eq_u32_e64 s[0:1], 15, v71
	v_writelane_b32 v254, s41, 34
	v_cmp_gt_u32_e64 s[40:41], v54, v3
	v_cndmask_b32_e64 v107, 0, 1.0, s[0:1]
	v_cmp_ne_u32_e64 s[0:1], v57, v37
	v_writelane_b32 v254, s40, 35
	v_or_b32_e32 v54, 3, v45
	v_cndmask_b32_e64 v59, 1, 2, s[0:1]
	v_subb_co_u32_e64 v57, s[0:1], v57, v37, s[0:1]
	v_or_b32_e32 v148, 8, v45
	v_mul_u32_u24_e32 v5, 0x210, v2
	s_movk_i32 s3, 0x310
	v_add_u32_e32 v89, s36, v56
	v_writelane_b32 v254, s41, 36
	v_add_u32_e32 v90, s37, v56
	v_cmp_ge_u32_e64 s[40:41], v54, v3
	v_lshlrev_b32_e32 v56, 2, v54
	v_cmp_gt_u32_e64 s[0:1], v54, v3
	v_lshlrev_b32_e32 v54, 2, v148
	v_or_b32_e32 v149, 9, v45
	v_add3_u32 v80, s27, v5, v52
	v_mul_lo_u32 v5, v53, s3
	v_add_u32_e32 v109, s36, v54
	v_add_u32_e32 v110, s37, v54
	v_lshlrev_b32_e32 v54, 2, v149
	v_or_b32_e32 v150, 10, v45
	v_add_u32_e32 v5, 0, v5
	v_lshlrev_b32_e32 v52, 2, v39
	v_add_u32_e32 v111, s36, v54
	v_add_u32_e32 v112, s37, v54
	v_lshlrev_b32_e32 v54, 2, v150
	v_or_b32_e32 v151, 11, v45
	v_add3_u32 v81, v5, v12, v52
	v_mul_lo_u32 v5, v55, s3
	v_add_u32_e32 v113, s36, v54
	v_add_u32_e32 v114, s37, v54
	v_lshlrev_b32_e32 v54, 2, v151
	v_or_b32_e32 v152, 16, v45
	v_add_u32_e32 v5, 0, v5
	v_lshlrev_b32_e32 v52, 2, v46
	v_add_u32_e32 v115, s36, v54
	v_add_u32_e32 v116, s37, v54
	v_lshlrev_b32_e32 v54, 2, v152
	v_or_b32_e32 v153, 17, v45
	v_add3_u32 v82, v5, v6, v52
	v_mul_lo_u32 v5, v60, s3
	v_add_u32_e32 v117, s36, v54
	v_add_u32_e32 v118, s37, v54
	v_lshlrev_b32_e32 v54, 2, v153
	v_or_b32_e32 v154, 18, v45
	v_add_u32_e32 v5, 0, v5
	v_lshlrev_b32_e32 v52, 2, v48
	v_add_u32_e32 v119, s36, v54
	v_add_u32_e32 v120, s37, v54
	v_lshlrev_b32_e32 v54, 2, v154
	v_or_b32_e32 v155, 19, v45
	v_add3_u32 v83, v5, v8, v52
	v_mul_lo_u32 v5, v61, s3
	v_add_u32_e32 v121, s36, v54
	v_add_u32_e32 v122, s37, v54
	v_lshlrev_b32_e32 v54, 2, v155
	v_or_b32_e32 v156, 24, v45
	v_add_u32_e32 v5, 0, v5
	v_lshlrev_b32_e32 v52, 2, v50
	v_add_u32_e32 v123, s36, v54
	v_add_u32_e32 v124, s37, v54
	v_lshlrev_b32_e32 v54, 2, v156
	v_or_b32_e32 v157, 25, v45
	v_add3_u32 v84, v5, v10, v52
	v_lshlrev_b32_e32 v5, 2, v45
	v_add_u32_e32 v125, s36, v54
	v_add_u32_e32 v126, s37, v54
	v_lshlrev_b32_e32 v54, 2, v157
	v_or_b32_e32 v158, 26, v45
	v_or_b32_e32 v159, 27, v45
	v_and_b32_e32 v49, -16, v37
	v_cmp_ge_u32_e64 s[34:35], v45, v3
	v_add_u32_e32 v85, s36, v5
	v_add_u32_e32 v86, s37, v5
	v_mul_u32_u24_e32 v5, 0x110, v45
	v_writelane_b32 v254, s40, 37
	v_add_u32_e32 v127, s36, v54
	v_add_u32_e32 v128, s37, v54
	v_lshlrev_b32_e32 v54, 2, v158
	v_lshlrev_b32_e32 v45, 2, v159
	v_add_u32_e32 v64, s36, v63
	v_add_u32_e32 v65, s37, v63
	v_lshl_add_u32 v72, v49, 2, 0
	v_lshlrev_b32_e32 v40, 6, v44
	v_writelane_b32 v254, s41, 38
	v_add_u32_e32 v91, s36, v56
	v_add_u32_e32 v108, s37, v56
	v_add_u32_e32 v129, s36, v54
	v_add_u32_e32 v130, s37, v54
	v_add_u32_e32 v131, s36, v45
	v_add_u32_e32 v132, s37, v45
	v_mul_lo_u32 v134, v49, s79
	v_lshlrev_b32_e32 v49, 1, v37
	v_and_or_b32 v44, v44, s38, v47
	v_add_u32_e32 v137, s36, v51
	v_readlane_b32 s36, v253, 32
	v_ashrrev_i32_e32 v13, 31, v12
	v_or_b32_e32 v45, 15, v37
	v_and_b32_e32 v49, 0x180, v49
	v_lshlrev_b32_e32 v54, 2, v36
	v_readlane_b32 s38, v253, 34
	v_readlane_b32 s39, v253, 35
	v_ashrrev_i32_e32 v7, 31, v6
	v_mul_lo_u32 v135, v45, s79
	v_mul_u32_u24_e32 v45, 0x84, v47
	v_add3_u32 v145, s27, v49, v54
	v_lshl_add_u64 v[12:13], v[12:13], 1, s[38:39]
	s_lshl_b32 s88, s26, 1
	v_lshl_add_u32 v136, v45, 2, v145
	v_mul_lo_u32 v146, v44, s64
	v_lshl_add_u64 v[12:13], v[12:13], 0, s[88:89]
	v_lshlrev_b32_e32 v44, 1, v39
	v_mov_b32_e32 v45, v0
	v_lshl_add_u64 v[6:7], v[6:7], 1, s[38:39]
	v_ashrrev_i32_e32 v9, 31, v8
	v_lshl_add_u64 v[44:45], v[12:13], 0, v[44:45]
	v_lshl_add_u64 v[6:7], v[6:7], 0, s[88:89]
	v_lshlrev_b32_e32 v12, 1, v46
	v_mov_b32_e32 v13, v0
	v_lshl_add_u64 v[46:47], v[6:7], 0, v[12:13]
	v_lshl_add_u64 v[6:7], v[8:9], 1, s[38:39]
	v_ashrrev_i32_e32 v11, 31, v10
	v_lshl_add_u64 v[6:7], v[6:7], 0, s[88:89]
	v_lshlrev_b32_e32 v8, 1, v48
	v_mov_b32_e32 v9, v0
	v_writelane_b32 v254, s0, 39
	v_lshl_add_u64 v[48:49], v[6:7], 0, v[8:9]
	v_lshl_add_u64 v[6:7], v[10:11], 1, s[38:39]
	v_writelane_b32 v254, s1, 40
	v_lshl_add_u64 v[6:7], v[6:7], 0, s[88:89]
	v_lshlrev_b32_e32 v8, 1, v50
	s_mov_b32 s0, 0xaaaaaaab
	v_lshl_add_u64 v[50:51], v[6:7], 0, v[8:9]
	v_mul_hi_u32 v7, v57, s0
	v_lshrrev_b32_e32 v7, 8, v7
	v_add_u32_e32 v7, v59, v7
	v_readlane_b32 s40, v253, 36
	v_and_b32_e32 v140, 0x1fffffe, v7
	s_movk_i32 s0, 0x180
	v_readlane_b32 s41, v253, 37
	v_mad_u64_u32 v[56:57], s[0:1], v140, s0, v[38:39]
	s_add_u32 s86, s40, s2
	v_lshrrev_b32_e32 v58, 1, v37
	s_addc_u32 s87, s41, 0
	s_add_i32 s0, 0, 0x1dc30
	v_mul_u32_u24_e32 v15, 0x110, v3
	v_lshl_add_u32 v57, v37, 4, s0
	v_and_b32_e32 v8, 16, v58
	s_movk_i32 s0, 0x1140
	v_add3_u32 v142, v15, v8, s52
	v_mul_lo_u32 v8, v68, s0
	v_mad_u32_u24 v8, v71, s79, v8
	v_lshlrev_b32_e32 v9, 4, v16
	s_mov_b32 s0, 0x9900
	v_add3_u32 v143, v8, v9, s0
	s_movk_i32 s0, 0x1100
	v_mul_lo_u32 v8, v68, s0
	v_cmp_gt_u32_e64 s[0:1], v148, v3
	v_cmp_gt_u32_e64 s[2:3], v159, v3
	v_add_u32_e32 v139, s77, v17
	v_writelane_b32 v254, s0, 41
	v_and_b32_e32 v6, 0xffffffc0, v37
	v_mul_u32_u24_e32 v9, 0x440, v16
	v_writelane_b32 v254, s1, 42
	v_cmp_ge_u32_e64 s[0:1], v149, v3
	v_lshlrev_b32_e32 v52, 2, v42
	v_mul_u32_u24_e32 v147, 0x110, v2
	v_writelane_b32 v254, s0, 43
	v_readlane_b32 s37, v253, 33
	v_add_u32_e32 v54, v139, v6
	v_writelane_b32 v254, s1, 44
	v_cmp_gt_u32_e64 s[0:1], v149, v3
	v_add3_u32 v6, v8, v9, v6
	v_mov_b32_e32 v35, s31
	v_writelane_b32 v254, s0, 45
	v_or_b32_e32 v34, s30, v42
	v_cmp_gt_i32_e64 s[12:13], 64, v37
	v_writelane_b32 v254, s1, 46
	v_cmp_ge_u32_e64 s[0:1], v150, v3
	v_cmp_lt_i32_e64 s[14:15], 63, v37
	v_cmp_gt_i32_e64 s[16:17], s16, v37
	v_writelane_b32 v254, s0, 47
	v_cmp_lt_i32_e64 s[18:19], 5, v68
	s_mov_b32 s78, 0
	v_writelane_b32 v254, s1, 48
	v_cmp_gt_u32_e64 s[0:1], v150, v3
	v_sub_u32_e32 v73, 4, v68
	v_lshlrev_b32_e32 v74, 2, v16
	v_writelane_b32 v254, s0, 49
	v_ashrrev_i32_e32 v41, 31, v40
	v_add_u32_e32 v42, 0, v52
	v_writelane_b32 v254, s1, 50
	v_cmp_ge_u32_e64 s[0:1], v151, v3
	v_add_u32_e32 v133, s77, v63
	v_add_u32_e32 v138, 16, v137
	v_writelane_b32 v254, s0, 51
	v_add_u32_e32 v52, s27, v52
	v_add_u32_e32 v39, 0x180, v38
	v_writelane_b32 v254, s1, 52
	v_cmp_gt_u32_e64 s[0:1], v151, v3
	v_add_u32_e32 v141, 0xfffffe00, v37
	v_or_b32_e32 v144, v6, v17
	v_writelane_b32 v254, s0, 53
	v_add_u32_e32 v145, v145, v146
	v_lshlrev_b32_e32 v58, 1, v2
	v_writelane_b32 v254, s1, 54
	v_cmp_gt_u32_e64 s[0:1], v152, v3
	v_add_u32_e32 v146, v4, v147
	v_add_u32_e32 v147, v14, v5
	v_writelane_b32 v254, s0, 55
	v_cmp_ge_u32_e64 s[36:37], v148, v3
	v_cmp_ge_u32_e64 s[70:71], v152, v3
	v_writelane_b32 v254, s1, 56
	v_cmp_gt_u32_e64 s[0:1], v153, v3
	v_cmp_ge_u32_e64 s[68:69], v153, v3
	v_cmp_ge_u32_e64 s[58:59], v154, v3
	v_writelane_b32 v254, s0, 57
	v_cmp_ge_u32_e64 s[62:63], v155, v3
	v_cmp_ge_u32_e64 s[66:67], v156, v3
	v_writelane_b32 v254, s1, 58
	v_cmp_gt_u32_e64 s[0:1], v154, v3
	v_cmp_ge_u32_e64 s[20:21], v157, v3
	v_cmp_ge_u32_e64 s[26:27], v158, v3
	v_writelane_b32 v254, s0, 59
	s_waitcnt vmcnt(0)
	v_readlane_b32 s42, v253, 38
	v_readlane_b32 s43, v253, 39
	v_writelane_b32 v254, s1, 60
	v_cmp_gt_u32_e64 s[0:1], v155, v3
	v_readlane_b32 s44, v253, 40
	v_readlane_b32 s45, v253, 41
	v_writelane_b32 v254, s0, 61
	v_readlane_b32 s46, v253, 42
	v_readlane_b32 s47, v253, 43
	v_writelane_b32 v254, s1, 62
	v_cmp_gt_u32_e64 s[0:1], v156, v3
	v_readlane_b32 s48, v253, 44
	v_readlane_b32 s49, v253, 45
	v_writelane_b32 v254, s0, 63
	v_readlane_b32 s50, v253, 46
	v_readlane_b32 s51, v253, 47
	v_writelane_b32 v255, s1, 0
	v_cmp_gt_u32_e64 s[0:1], v157, v3
	s_nop 1
	v_writelane_b32 v255, s0, 1
	s_nop 1
	v_writelane_b32 v255, s1, 2
	v_cmp_gt_u32_e64 s[0:1], v158, v3
	s_nop 1
	v_writelane_b32 v255, s0, 3
	s_nop 1
	v_writelane_b32 v255, s1, 4
	v_writelane_b32 v255, s2, 5
	v_cmp_ge_u32_e64 s[0:1], v159, v3
	s_nop 0
	v_writelane_b32 v255, s3, 6
	v_cmp_lt_u32_e64 s[2:3], 1, v7
	s_nop 1
	v_writelane_b32 v255, s2, 7
	s_nop 1
	v_writelane_b32 v255, s3, 8
	v_cmp_ne_u32_e64 s[2:3], v7, v140
	s_nop 1
	v_writelane_b32 v255, s2, 9
	s_nop 1
	v_writelane_b32 v255, s3, 10
	s_branch .LBB0_294
	s_nop 0

.LBB0_475:
	ds_read_b128 v[148:151], v76
	ds_read2_b32 v[152:153], v136 offset1:132
	v_add_u32_e32 v59, 0x400, v136
	ds_read2_b32 v[244:245], v59 offset0:8 offset1:140
	ds_read_b128 v[238:241], v76 offset:32
	v_add_u32_e32 v59, 0x1000, v136
	ds_read2_b32 v[242:243], v59 offset0:32 offset1:164
	v_add_u32_e32 v59, 0x1400, v136
	ds_read2_b32 v[246:247], v59 offset0:40 offset1:172
	s_waitcnt lgkmcnt(4)
	v_mfma_f32_32x32x2_f32 v[2:17], v148, v152, 0
	v_mfma_f32_32x32x2_f32 v[2:17], v149, v153, v[2:17]
	s_waitcnt lgkmcnt(3)
	v_mfma_f32_32x32x2_f32 v[2:17], v150, v244, v[2:17]
	v_mfma_f32_32x32x2_f32 v[2:17], v151, v245, v[2:17]
	ds_read_b128 v[148:151], v76 offset:64
	v_add_u32_e32 v59, 0x2000, v136
	ds_read2_b32 v[152:153], v59 offset0:64 offset1:196
	v_add_u32_e32 v59, 0x2400, v136
	ds_read2_b32 v[244:245], v59 offset0:72 offset1:204
	s_waitcnt lgkmcnt(4)
	v_mfma_f32_32x32x2_f32 v[2:17], v238, v242, v[2:17]
	v_mfma_f32_32x32x2_f32 v[2:17], v239, v243, v[2:17]
	s_waitcnt lgkmcnt(3)
	v_mfma_f32_32x32x2_f32 v[2:17], v240, v246, v[2:17]
	v_mfma_f32_32x32x2_f32 v[2:17], v241, v247, v[2:17]
	ds_read_b128 v[238:241], v76 offset:96
	v_add_u32_e32 v59, 0x3000, v136
	ds_read2_b32 v[242:243], v59 offset0:96 offset1:228
	v_add_u32_e32 v59, 0x3400, v136
	ds_read2_b32 v[246:247], v59 offset0:104 offset1:236
	s_waitcnt lgkmcnt(4)
	v_mfma_f32_32x32x2_f32 v[2:17], v148, v152, v[2:17]
	v_mfma_f32_32x32x2_f32 v[2:17], v149, v153, v[2:17]
	s_waitcnt lgkmcnt(3)
	v_mfma_f32_32x32x2_f32 v[2:17], v150, v244, v[2:17]
	v_mfma_f32_32x32x2_f32 v[2:17], v151, v245, v[2:17]
	s_waitcnt lgkmcnt(1)
	v_mfma_f32_32x32x2_f32 v[2:17], v238, v242, v[2:17]
	v_mfma_f32_32x32x2_f32 v[2:17], v239, v243, v[2:17]
	s_waitcnt lgkmcnt(0)
	v_mfma_f32_32x32x2_f32 v[2:17], v240, v246, v[2:17]
	v_mfma_f32_32x32x2_f32 v[2:17], v241, v247, v[2:17]
	s_and_saveexec_b64 s[2:3], s[24:25]
	s_cbranch_execz .LBB0_293
	ds_read_b128 v[148:151], v76 offset:128
	v_add_u32_e32 v59, 0x4200, v136
	ds_read2_b32 v[152:153], v59 offset1:132
	v_add_u32_e32 v59, 0x4600, v136
	ds_read2_b32 v[244:245], v59 offset0:8 offset1:140
	ds_read_b128 v[238:241], v76 offset:160
	v_add_u32_e32 v59, 0x5200, v136
	ds_read2_b32 v[242:243], v59 offset0:32 offset1:164
	v_add_u32_e32 v59, 0x5600, v136
	ds_read2_b32 v[246:247], v59 offset0:40 offset1:172
	s_waitcnt lgkmcnt(4)
	v_mfma_f32_32x32x2_f32 v[2:17], v148, v152, v[2:17]
	v_mfma_f32_32x32x2_f32 v[2:17], v149, v153, v[2:17]
	s_waitcnt lgkmcnt(3)
	v_mfma_f32_32x32x2_f32 v[2:17], v150, v244, v[2:17]
	v_mfma_f32_32x32x2_f32 v[2:17], v151, v245, v[2:17]
	ds_read_b128 v[148:151], v76 offset:192
	v_add_u32_e32 v59, 0x6200, v136
	ds_read2_b32 v[152:153], v59 offset0:64 offset1:196
	v_add_u32_e32 v59, 0x6600, v136
	ds_read2_b32 v[244:245], v59 offset0:72 offset1:204
	s_waitcnt lgkmcnt(4)
	v_mfma_f32_32x32x2_f32 v[2:17], v238, v242, v[2:17]
	v_mfma_f32_32x32x2_f32 v[2:17], v239, v243, v[2:17]
	s_waitcnt lgkmcnt(3)
	v_mfma_f32_32x32x2_f32 v[2:17], v240, v246, v[2:17]
	v_mfma_f32_32x32x2_f32 v[2:17], v241, v247, v[2:17]
	ds_read_b128 v[238:241], v76 offset:224
	v_add_u32_e32 v59, 0x7200, v136
	ds_read2_b32 v[242:243], v59 offset0:96 offset1:228
	v_add_u32_e32 v59, 0x7600, v136
	ds_read2_b32 v[246:247], v59 offset0:104 offset1:236
	s_waitcnt lgkmcnt(4)
	v_mfma_f32_32x32x2_f32 v[2:17], v148, v152, v[2:17]
	v_mfma_f32_32x32x2_f32 v[2:17], v149, v153, v[2:17]
	s_waitcnt lgkmcnt(3)
	v_mfma_f32_32x32x2_f32 v[2:17], v150, v244, v[2:17]
	v_mfma_f32_32x32x2_f32 v[2:17], v151, v245, v[2:17]
	s_waitcnt lgkmcnt(1)
	v_mfma_f32_32x32x2_f32 v[2:17], v238, v242, v[2:17]
	v_mfma_f32_32x32x2_f32 v[2:17], v239, v243, v[2:17]
	s_waitcnt lgkmcnt(0)
	v_mfma_f32_32x32x2_f32 v[2:17], v240, v246, v[2:17]
	v_mfma_f32_32x32x2_f32 v[2:17], v241, v247, v[2:17]
	s_branch .LBB0_293
	s_nop 0
